# attention loops: lazy softmax rescale - the accumulator/row-sum rescale is skipped (wave-uniform) while the running max grows by less than 8 in log2 units, reference max kept; falls back to the full u
# baseline (speedup 1.0000x reference)
.Llat1_maxdone:
	ds_bpermute_b32 v237, v155, v236
	s_waitcnt lgkmcnt(0)
	v_max3_f32 v236, v183, v236, v237
	v_sub_f32_e32 v238, v183, v236
	v_mov_b32_e32 v239, 0xc1000000
	v_cmp_gt_f32_e64 s[70:71], v239, v238
	s_cmp_lg_u64 s[70:71], 0
	s_cbranch_scc1 .Lzfull_lat1
	v_mov_b32_e32 v236, v183
	v_mov_b32_e32 v238, 0
.Lzfull_lat1:
	v_sub_f32_e32 v48, v48, v236
	v_sub_f32_e32 v49, v49, v236
	v_sub_f32_e32 v50, v50, v236
	v_sub_f32_e32 v51, v51, v236
	v_sub_f32_e32 v52, v52, v236
	v_sub_f32_e32 v53, v53, v236
	v_sub_f32_e32 v54, v54, v236
	v_sub_f32_e32 v55, v55, v236
	v_sub_f32_e32 v56, v56, v236
	v_sub_f32_e32 v57, v57, v236
	v_sub_f32_e32 v58, v58, v236
	v_sub_f32_e32 v59, v59, v236
	v_sub_f32_e32 v60, v60, v236
	v_sub_f32_e32 v61, v61, v236
	v_sub_f32_e32 v62, v62, v236
	v_sub_f32_e32 v63, v63, v236
	v_exp_f32_e32 v238, v238
	v_exp_f32_e32 v48, v48
	v_exp_f32_e32 v49, v49
	v_exp_f32_e32 v50, v50
	v_exp_f32_e32 v51, v51
	v_exp_f32_e32 v52, v52
	v_exp_f32_e32 v53, v53
	v_exp_f32_e32 v54, v54
	v_exp_f32_e32 v55, v55
	v_exp_f32_e32 v56, v56
	v_exp_f32_e32 v57, v57
	v_exp_f32_e32 v58, v58
	v_exp_f32_e32 v59, v59
	v_exp_f32_e32 v60, v60
	v_exp_f32_e32 v61, v61
	v_exp_f32_e32 v62, v62
	v_exp_f32_e32 v63, v63
	v_add_f32_e32 v242, 0, v48
	v_add_f32_e32 v243, 0, v49
	v_add_f32_e32 v242, v50, v242
	v_add_f32_e32 v243, v51, v243
	v_add_f32_e32 v242, v52, v242
	v_add_f32_e32 v243, v53, v243
	v_add_f32_e32 v242, v54, v242
	v_add_f32_e32 v243, v55, v243
	v_add_f32_e32 v242, v56, v242
	v_add_f32_e32 v243, v57, v243
	v_add_f32_e32 v242, v58, v242
	v_add_f32_e32 v243, v59, v243
	v_add_f32_e32 v242, v60, v242
	v_add_f32_e32 v243, v61, v243
	v_add_f32_e32 v242, v62, v242
	v_add_f32_e32 v243, v63, v243
	v_cvt_pk_bf16_f32 v48, v48, v49
	v_cvt_pk_bf16_f32 v49, v50, v51
	v_cvt_pk_bf16_f32 v50, v52, v53
	v_cvt_pk_bf16_f32 v51, v54, v55
	v_cvt_pk_bf16_f32 v52, v56, v57
	v_cvt_pk_bf16_f32 v53, v58, v59
	v_cvt_pk_bf16_f32 v54, v60, v61
	v_cvt_pk_bf16_f32 v55, v62, v63
	s_cmp_lg_u64 s[70:71], 0
	s_cbranch_scc0 .Lzskip_lat1
	v_mul_f32_e32 v16, v16, v238
	v_mul_f32_e32 v17, v17, v238
	v_mul_f32_e32 v18, v18, v238
	v_mul_f32_e32 v19, v19, v238
	v_mul_f32_e32 v20, v20, v238
	v_mul_f32_e32 v21, v21, v238
	v_mul_f32_e32 v22, v22, v238
	v_mul_f32_e32 v23, v23, v238
	v_mul_f32_e32 v24, v24, v238
	v_mul_f32_e32 v25, v25, v238
	v_mul_f32_e32 v26, v26, v238
	v_mul_f32_e32 v27, v27, v238
	v_mul_f32_e32 v28, v28, v238
	v_mul_f32_e32 v29, v29, v238
	v_mul_f32_e32 v30, v30, v238
	v_mul_f32_e32 v31, v31, v238
	v_mul_f32_e32 v0, v0, v238
	v_mul_f32_e32 v1, v1, v238
	v_mul_f32_e32 v2, v2, v238
	v_mul_f32_e32 v3, v3, v238
	v_mul_f32_e32 v4, v4, v238
	v_mul_f32_e32 v5, v5, v238
	v_mul_f32_e32 v6, v6, v238
	v_mul_f32_e32 v7, v7, v238
	v_mul_f32_e32 v8, v8, v238
	v_mul_f32_e32 v9, v9, v238
	v_mul_f32_e32 v10, v10, v238
	v_mul_f32_e32 v11, v11, v238
	v_mul_f32_e32 v12, v12, v238
	v_mul_f32_e32 v13, v13, v238
	v_mul_f32_e32 v14, v14, v238
	v_mul_f32_e32 v15, v15, v238
.Lzskip_lat1:
	v_mfma_f32_32x32x16_bf16 v[16:31], v[202:205], v[48:51], v[16:31]
	ds_read_b128 v[202:205], v129
	v_sub_f32_e32 v32, v32, v236
	v_sub_f32_e32 v33, v33, v236
	v_sub_f32_e32 v34, v34, v236
	v_sub_f32_e32 v35, v35, v236
	v_sub_f32_e32 v36, v36, v236
	v_sub_f32_e32 v37, v37, v236
	v_sub_f32_e32 v38, v38, v236
	v_sub_f32_e32 v39, v39, v236
	v_sub_f32_e32 v40, v40, v236
	v_sub_f32_e32 v41, v41, v236
	v_sub_f32_e32 v42, v42, v236
	v_sub_f32_e32 v43, v43, v236
	v_sub_f32_e32 v44, v44, v236
	v_sub_f32_e32 v45, v45, v236
	v_sub_f32_e32 v46, v46, v236
	v_sub_f32_e32 v47, v47, v236
	v_exp_f32_e32 v32, v32
	v_exp_f32_e32 v33, v33
	v_mfma_f32_32x32x16_bf16 v[16:31], v[206:209], v[52:55], v[16:31]
	ds_read_b128 v[206:209], v129 offset:32
	v_exp_f32_e32 v34, v34
	v_exp_f32_e32 v35, v35
	v_exp_f32_e32 v36, v36
	v_exp_f32_e32 v37, v37
	v_exp_f32_e32 v38, v38
	v_exp_f32_e32 v39, v39
	v_exp_f32_e32 v40, v40
	v_exp_f32_e32 v41, v41
	v_exp_f32_e32 v42, v42
	v_exp_f32_e32 v43, v43
	v_mfma_f32_32x32x16_bf16 v[0:15], v[210:213], v[48:51], v[0:15]
	ds_read_b128 v[210:213], v129 offset:64
	v_exp_f32_e32 v44, v44
	v_exp_f32_e32 v45, v45
	v_exp_f32_e32 v46, v46
	v_exp_f32_e32 v47, v47
	v_add_f32_e32 v242, v32, v242
	v_add_f32_e32 v243, v33, v243
	v_add_f32_e32 v242, v34, v242
	v_add_f32_e32 v243, v35, v243
	v_add_f32_e32 v242, v36, v242
	v_add_f32_e32 v243, v37, v243
	v_add_f32_e32 v242, v38, v242
	v_add_f32_e32 v243, v39, v243
	v_add_f32_e32 v242, v40, v242
	v_add_f32_e32 v243, v41, v243
	v_add_f32_e32 v242, v42, v242
	v_add_f32_e32 v243, v43, v243
	v_mfma_f32_32x32x16_bf16 v[0:15], v[214:217], v[52:55], v[0:15]
	ds_read_b128 v[214:217], v129 offset:96
	v_add_f32_e32 v242, v44, v242
	v_add_f32_e32 v243, v45, v243
	v_add_f32_e32 v242, v46, v242
	v_add_f32_e32 v243, v47, v243
	v_cvt_pk_bf16_f32 v32, v32, v33
	v_cvt_pk_bf16_f32 v33, v34, v35
	v_cvt_pk_bf16_f32 v34, v36, v37
	v_cvt_pk_bf16_f32 v35, v38, v39
	v_cvt_pk_bf16_f32 v36, v40, v41
	v_cvt_pk_bf16_f32 v37, v42, v43
	v_cvt_pk_bf16_f32 v38, v44, v45
	v_cvt_pk_bf16_f32 v39, v46, v47
	v_add_f32_e32 v242, v242, v243
	v_fmac_f32_e32 v242, v182, v238
	v_mfma_f32_32x32x16_bf16 v[16:31], v[218:221], v[32:35], v[16:31]
	ds_read_b128 v[218:221], v129 offset:4608
	v_mfma_f32_32x32x16_bf16 v[16:31], v[222:225], v[36:39], v[16:31]
	ds_read_b128 v[222:225], v129 offset:4640
	v_mfma_f32_32x32x16_bf16 v[0:15], v[226:229], v[32:35], v[0:15]
	ds_read_b128 v[226:229], v129 offset:4672
	v_mfma_f32_32x32x16_bf16 v[0:15], v[230:233], v[36:39], v[0:15]
	ds_read_b128 v[230:233], v129 offset:4704
	v_mov_b32_e32 v182, v242
	v_mov_b32_e32 v183, v236
	v_add_u32_e32 v129, 0x2400, v129
	v_add_u32_e32 v234, 0x3000, v234
	s_add_i32 s19, s19, 64
	v_subrev_u32_e32 v179, 64, v179
	v_add_u32_e32 v180, 64, v180
	s_add_i32 s21, s21, -1
	s_cmp_lg_u32 s21, 0
	s_cbranch_scc1 .Llat1_top
	v_mov_b32_e32 v54, v182
	v_mov_b32_e32 v156, v183
	s_branch .LBB0_387

.Llat2_top:
	s_waitcnt lgkmcnt(7)
	v_mfma_f32_32x32x16_bf16 v[48:63], v[202:205], v[96:99], 0
	ds_read_b64_tr_b16 v[202:203], v234 offset:46080
	ds_read_b64_tr_b16 v[204:205], v234 offset:47616
	s_waitcnt lgkmcnt(8)
	v_mfma_f32_32x32x16_bf16 v[48:63], v[206:209], v[100:103], v[48:63]
	ds_read_b64_tr_b16 v[206:207], v234 offset:49152
	ds_read_b64_tr_b16 v[208:209], v234 offset:50688
	s_waitcnt lgkmcnt(9)
	v_mfma_f32_32x32x16_bf16 v[48:63], v[210:213], v[104:107], v[48:63]
	ds_read_b64_tr_b16 v[210:211], v234 offset:46144
	ds_read_b64_tr_b16 v[212:213], v234 offset:47680
	s_waitcnt lgkmcnt(10)
	v_mfma_f32_32x32x16_bf16 v[48:63], v[214:217], v[108:111], v[48:63]
	ds_read_b64_tr_b16 v[214:215], v234 offset:49216
	ds_read_b64_tr_b16 v[216:217], v234 offset:50752
	s_waitcnt lgkmcnt(11)
	v_mfma_f32_32x32x16_bf16 v[32:47], v[218:221], v[96:99], 0
	ds_read_b64_tr_b16 v[218:219], v234 offset:52224
	ds_read_b64_tr_b16 v[220:221], v234 offset:53760
	s_waitcnt lgkmcnt(12)
	v_mfma_f32_32x32x16_bf16 v[32:47], v[222:225], v[100:103], v[32:47]
	ds_read_b64_tr_b16 v[222:223], v234 offset:55296
	ds_read_b64_tr_b16 v[224:225], v234 offset:56832
	s_waitcnt lgkmcnt(13)
	v_mfma_f32_32x32x16_bf16 v[32:47], v[226:229], v[104:107], v[32:47]
	ds_read_b64_tr_b16 v[226:227], v234 offset:52288
	ds_read_b64_tr_b16 v[228:229], v234 offset:53824
	s_waitcnt lgkmcnt(13)
	v_mfma_f32_32x32x16_bf16 v[32:47], v[230:233], v[108:111], v[32:47]
	ds_read_b64_tr_b16 v[230:231], v234 offset:55360
	ds_read_b64_tr_b16 v[232:233], v234 offset:56896
	v_max3_f32 v236, v48, s16, v49
	v_max3_f32 v236, v236, v50, v51
	v_max3_f32 v236, v236, v52, v53
	v_max3_f32 v236, v236, v54, v55
	v_max3_f32 v236, v236, v56, v57
	v_max3_f32 v236, v236, v58, v59
	v_max3_f32 v236, v236, v60, v61
	v_max3_f32 v236, v236, v62, v63
	s_nop 3
	v_max3_f32 v236, v236, v32, v33
	v_max3_f32 v236, v236, v34, v35
	v_max3_f32 v236, v236, v36, v37
	v_max3_f32 v236, v236, v38, v39
	v_max3_f32 v236, v236, v40, v41
	v_max3_f32 v236, v236, v42, v43
	v_max3_f32 v236, v236, v44, v45
	v_max3_f32 v236, v236, v46, v47
	ds_bpermute_b32 v237, v113, v236
	s_waitcnt lgkmcnt(0)
	v_max3_f32 v236, v156, v236, v237
	v_sub_f32_e32 v238, v156, v236
	v_mov_b32_e32 v239, 0xc1000000
	v_cmp_gt_f32_e64 s[70:71], v239, v238
	s_cmp_lg_u64 s[70:71], 0
	s_cbranch_scc1 .Lzfull_lat2
	v_mov_b32_e32 v236, v156
	v_mov_b32_e32 v238, 0

.Lzskip_lat2:
	v_mfma_f32_32x32x16_bf16 v[16:31], v[202:205], v[48:51], v[16:31]
	ds_read_b128 v[202:205], v127
	v_sub_f32_e32 v32, v32, v236
	v_sub_f32_e32 v33, v33, v236
	v_sub_f32_e32 v34, v34, v236
	v_sub_f32_e32 v35, v35, v236
	v_sub_f32_e32 v36, v36, v236
	v_sub_f32_e32 v37, v37, v236
	v_sub_f32_e32 v38, v38, v236
	v_sub_f32_e32 v39, v39, v236
	v_sub_f32_e32 v40, v40, v236
	v_sub_f32_e32 v41, v41, v236
	v_sub_f32_e32 v42, v42, v236
	v_sub_f32_e32 v43, v43, v236
	v_sub_f32_e32 v44, v44, v236
	v_sub_f32_e32 v45, v45, v236
	v_sub_f32_e32 v46, v46, v236
	v_sub_f32_e32 v47, v47, v236
	v_exp_f32_e32 v32, v32
	v_exp_f32_e32 v33, v33
	v_mfma_f32_32x32x16_bf16 v[16:31], v[206:209], v[52:55], v[16:31]
	ds_read_b128 v[206:209], v127 offset:32
	v_exp_f32_e32 v34, v34
	v_exp_f32_e32 v35, v35
	v_exp_f32_e32 v36, v36
	v_exp_f32_e32 v37, v37
	v_exp_f32_e32 v38, v38
	v_exp_f32_e32 v39, v39
	v_exp_f32_e32 v40, v40
	v_exp_f32_e32 v41, v41
	v_exp_f32_e32 v42, v42
	v_exp_f32_e32 v43, v43
	v_mfma_f32_32x32x16_bf16 v[0:15], v[210:213], v[48:51], v[0:15]
	ds_read_b128 v[210:213], v127 offset:64
	v_exp_f32_e32 v44, v44
	v_exp_f32_e32 v45, v45
	v_exp_f32_e32 v46, v46
	v_exp_f32_e32 v47, v47
	v_add_f32_e32 v242, v32, v242
	v_add_f32_e32 v243, v33, v243
	v_add_f32_e32 v242, v34, v242
	v_add_f32_e32 v243, v35, v243
	v_add_f32_e32 v242, v36, v242
	v_add_f32_e32 v243, v37, v243
	v_add_f32_e32 v242, v38, v242
	v_add_f32_e32 v243, v39, v243
	v_add_f32_e32 v242, v40, v242
	v_add_f32_e32 v243, v41, v243
	v_add_f32_e32 v242, v42, v242
	v_add_f32_e32 v243, v43, v243
	v_mfma_f32_32x32x16_bf16 v[0:15], v[214:217], v[52:55], v[0:15]
	ds_read_b128 v[214:217], v127 offset:96
	v_add_f32_e32 v242, v44, v242
	v_add_f32_e32 v243, v45, v243
	v_add_f32_e32 v242, v46, v242
	v_add_f32_e32 v243, v47, v243
	v_cvt_pk_bf16_f32 v32, v32, v33
	v_cvt_pk_bf16_f32 v33, v34, v35
	v_cvt_pk_bf16_f32 v34, v36, v37
	v_cvt_pk_bf16_f32 v35, v38, v39
	v_cvt_pk_bf16_f32 v36, v40, v41
	v_cvt_pk_bf16_f32 v37, v42, v43
	v_cvt_pk_bf16_f32 v38, v44, v45
	v_cvt_pk_bf16_f32 v39, v46, v47
	v_add_f32_e32 v242, v242, v243
	v_fmac_f32_e32 v242, v244, v238
	v_mfma_f32_32x32x16_bf16 v[16:31], v[218:221], v[32:35], v[16:31]
	ds_read_b128 v[218:221], v127 offset:4608
	v_mfma_f32_32x32x16_bf16 v[16:31], v[222:225], v[36:39], v[16:31]
	ds_read_b128 v[222:225], v127 offset:4640
	v_mfma_f32_32x32x16_bf16 v[0:15], v[226:229], v[32:35], v[0:15]
	ds_read_b128 v[226:229], v127 offset:4672
	v_mfma_f32_32x32x16_bf16 v[0:15], v[230:233], v[36:39], v[0:15]
	ds_read_b128 v[230:233], v127 offset:4704
	v_mov_b32_e32 v244, v242
	v_mov_b32_e32 v156, v236
	v_add_u32_e32 v127, 0x2400, v127
	v_add_u32_e32 v234, 0x3000, v234
	s_add_i32 s21, s21, -1
	s_cmp_lg_u32 s21, 0
	s_cbranch_scc1 .Llat2_top
	v_mov_b32_e32 v54, v244
	v_mov_b32_e32 v32, v251

.Lctx_top:
	s_waitcnt lgkmcnt(7)
	v_mfma_f32_32x32x16_bf16 v[48:63], v[202:205], v[96:99], 0
	ds_read_b64_tr_b16 v[202:203], v234 offset:46080
	ds_read_b64_tr_b16 v[204:205], v234 offset:47616
	s_waitcnt lgkmcnt(8)
	v_mfma_f32_32x32x16_bf16 v[48:63], v[206:209], v[100:103], v[48:63]
	ds_read_b64_tr_b16 v[206:207], v234 offset:49152
	ds_read_b64_tr_b16 v[208:209], v234 offset:50688
	s_waitcnt lgkmcnt(9)
	v_mfma_f32_32x32x16_bf16 v[48:63], v[210:213], v[104:107], v[48:63]
	ds_read_b64_tr_b16 v[210:211], v234 offset:46144
	ds_read_b64_tr_b16 v[212:213], v234 offset:47680
	s_waitcnt lgkmcnt(10)
	v_mfma_f32_32x32x16_bf16 v[48:63], v[214:217], v[108:111], v[48:63]
	ds_read_b64_tr_b16 v[214:215], v234 offset:49216
	ds_read_b64_tr_b16 v[216:217], v234 offset:50752
	s_waitcnt lgkmcnt(11)
	v_mfma_f32_32x32x16_bf16 v[32:47], v[218:221], v[96:99], 0
	ds_read_b64_tr_b16 v[218:219], v234 offset:52224
	ds_read_b64_tr_b16 v[220:221], v234 offset:53760
	s_waitcnt lgkmcnt(12)
	v_mfma_f32_32x32x16_bf16 v[32:47], v[222:225], v[100:103], v[32:47]
	ds_read_b64_tr_b16 v[222:223], v234 offset:55296
	ds_read_b64_tr_b16 v[224:225], v234 offset:56832
	s_waitcnt lgkmcnt(13)
	v_mfma_f32_32x32x16_bf16 v[32:47], v[226:229], v[104:107], v[32:47]
	ds_read_b64_tr_b16 v[226:227], v234 offset:52288
	ds_read_b64_tr_b16 v[228:229], v234 offset:53824
	s_waitcnt lgkmcnt(13)
	v_mfma_f32_32x32x16_bf16 v[32:47], v[230:233], v[108:111], v[32:47]
	ds_read_b64_tr_b16 v[230:231], v234 offset:55360
	ds_read_b64_tr_b16 v[232:233], v234 offset:56896
	v_max3_f32 v236, v48, s16, v49
	v_max3_f32 v236, v236, v50, v51
	v_max3_f32 v236, v236, v52, v53
	v_max3_f32 v236, v236, v54, v55
	v_max3_f32 v236, v236, v56, v57
	v_max3_f32 v236, v236, v58, v59
	v_max3_f32 v236, v236, v60, v61
	v_max3_f32 v236, v236, v62, v63
	s_nop 3
	v_max3_f32 v236, v236, v32, v33
	v_max3_f32 v236, v236, v34, v35
	v_max3_f32 v236, v236, v36, v37
	v_max3_f32 v236, v236, v38, v39
	v_max3_f32 v236, v236, v40, v41
	v_max3_f32 v236, v236, v42, v43
	v_max3_f32 v236, v236, v44, v45
	v_max3_f32 v236, v236, v46, v47
	ds_bpermute_b32 v237, v133, v236
	s_waitcnt lgkmcnt(0)
	v_max3_f32 v236, v137, v236, v237
	v_sub_f32_e32 v238, v137, v236
	v_mov_b32_e32 v239, 0xc1000000
	v_cmp_gt_f32_e64 s[70:71], v239, v238
	s_cmp_lg_u64 s[70:71], 0
	s_cbranch_scc1 .Lzfull_ctx
	v_mov_b32_e32 v236, v137
	v_mov_b32_e32 v238, 0

.Lzskip_ctx:
	v_mfma_f32_32x32x16_bf16 v[16:31], v[202:205], v[48:51], v[16:31]
	ds_read_b128 v[202:205], v136
	v_sub_f32_e32 v32, v32, v236
	v_sub_f32_e32 v33, v33, v236
	v_sub_f32_e32 v34, v34, v236
	v_sub_f32_e32 v35, v35, v236
	v_sub_f32_e32 v36, v36, v236
	v_sub_f32_e32 v37, v37, v236
	v_sub_f32_e32 v38, v38, v236
	v_sub_f32_e32 v39, v39, v236
	v_sub_f32_e32 v40, v40, v236
	v_sub_f32_e32 v41, v41, v236
	v_sub_f32_e32 v42, v42, v236
	v_sub_f32_e32 v43, v43, v236
	v_sub_f32_e32 v44, v44, v236
	v_sub_f32_e32 v45, v45, v236
	v_sub_f32_e32 v46, v46, v236
	v_sub_f32_e32 v47, v47, v236
	v_exp_f32_e32 v32, v32
	v_exp_f32_e32 v33, v33
	v_mfma_f32_32x32x16_bf16 v[16:31], v[206:209], v[52:55], v[16:31]
	ds_read_b128 v[206:209], v136 offset:32
	v_exp_f32_e32 v34, v34
	v_exp_f32_e32 v35, v35
	v_exp_f32_e32 v36, v36
	v_exp_f32_e32 v37, v37
	v_exp_f32_e32 v38, v38
	v_exp_f32_e32 v39, v39
	v_exp_f32_e32 v40, v40
	v_exp_f32_e32 v41, v41
	v_exp_f32_e32 v42, v42
	v_exp_f32_e32 v43, v43
	v_mfma_f32_32x32x16_bf16 v[0:15], v[210:213], v[48:51], v[0:15]
	ds_read_b128 v[210:213], v136 offset:64
	v_exp_f32_e32 v44, v44
	v_exp_f32_e32 v45, v45
	v_exp_f32_e32 v46, v46
	v_exp_f32_e32 v47, v47
	v_add_f32_e32 v242, v32, v242
	v_add_f32_e32 v243, v33, v243
	v_add_f32_e32 v242, v34, v242
	v_add_f32_e32 v243, v35, v243
	v_add_f32_e32 v242, v36, v242
	v_add_f32_e32 v243, v37, v243
	v_add_f32_e32 v242, v38, v242
	v_add_f32_e32 v243, v39, v243
	v_add_f32_e32 v242, v40, v242
	v_add_f32_e32 v243, v41, v243
	v_add_f32_e32 v242, v42, v242
	v_add_f32_e32 v243, v43, v243
	v_mfma_f32_32x32x16_bf16 v[0:15], v[214:217], v[52:55], v[0:15]
	ds_read_b128 v[214:217], v136 offset:96
	v_add_f32_e32 v242, v44, v242
	v_add_f32_e32 v243, v45, v243
	v_add_f32_e32 v242, v46, v242
	v_add_f32_e32 v243, v47, v243
	v_cvt_pk_bf16_f32 v32, v32, v33
	v_cvt_pk_bf16_f32 v33, v34, v35
	v_cvt_pk_bf16_f32 v34, v36, v37
	v_cvt_pk_bf16_f32 v35, v38, v39
	v_cvt_pk_bf16_f32 v36, v40, v41
	v_cvt_pk_bf16_f32 v37, v42, v43
	v_cvt_pk_bf16_f32 v38, v44, v45
	v_cvt_pk_bf16_f32 v39, v46, v47
	v_add_f32_e32 v242, v242, v243
	v_fmac_f32_e32 v242, v244, v238
	v_mfma_f32_32x32x16_bf16 v[16:31], v[218:221], v[32:35], v[16:31]
	ds_read_b128 v[218:221], v136 offset:4608
	v_mfma_f32_32x32x16_bf16 v[16:31], v[222:225], v[36:39], v[16:31]
	ds_read_b128 v[222:225], v136 offset:4640
	v_mfma_f32_32x32x16_bf16 v[0:15], v[226:229], v[32:35], v[0:15]
	ds_read_b128 v[226:229], v136 offset:4672
	v_mfma_f32_32x32x16_bf16 v[0:15], v[230:233], v[36:39], v[0:15]
	ds_read_b128 v[230:233], v136 offset:4704
	v_mov_b32_e32 v244, v242
	v_mov_b32_e32 v137, v236
	v_add_u32_e32 v136, 0x2400, v136
	v_add_u32_e32 v234, 0x3000, v234
	s_add_i32 s21, s21, -1
	s_cmp_lg_u32 s21, 0
	s_cbranch_scc1 .Lctx_top
	v_mov_b32_e32 v48, v244
	ds_bpermute_b32 v32, v133, v48
	s_add_u32 s0, s28, s6
	s_addc_u32 s1, s29, s7
	v_lshlrev_b64 v[34:35], 11, v[112:113]
	v_lshl_add_u64 v[34:35], s[0:1], 0, v[34:35]
	s_waitcnt lgkmcnt(0)
	v_add_f32_e32 v32, v48, v32
	v_rcp_f32_e32 v32, v32
	v_lshlrev_b32_e32 v198, 1, v132
	v_lshl_add_u64 v[36:37], v[34:35], 0, v[198:199]
	v_lshlrev_b32_e32 v34, 16, v130
	v_pk_mul_f32 v[38:39], v[16:17], v[32:33] op_sel_hi:[1,0]
	v_mul_f32_e32 v33, 0xbfb8aa3b, v34
	v_exp_f32_e32 v33, v33
	v_and_b32_e32 v35, 0xffff0000, v130
	v_pk_mul_f32 v[16:17], v[38:39], v[38:39]
	v_pk_mul_f32 v[38:39], v[92:93], v[38:39]
	v_add_f32_e32 v33, 1.0, v33
	v_rcp_f32_e32 v40, v33
	v_mul_f32_e32 v33, 0xbfb8aa3b, v35
	v_exp_f32_e32 v33, v33
	v_lshlrev_b32_e32 v198, 1, v128
	v_add_f32_e32 v16, v16, v17
	v_add_f32_e32 v33, 1.0, v33
	v_rcp_f32_e32 v41, v33
	v_pk_mul_f32 v[18:19], v[18:19], v[32:33] op_sel_hi:[1,0]
	v_pk_mul_f32 v[34:35], v[40:41], v[34:35]
	v_lshlrev_b32_e32 v40, 16, v131
	v_mul_f32_e32 v33, 0xbfb8aa3b, v40
	v_exp_f32_e32 v33, v33
	v_and_b32_e32 v41, 0xffff0000, v131
	v_pk_mul_f32 v[34:35], v[34:35], v[38:39]
	v_add_f32_e32 v33, 1.0, v33
	v_rcp_f32_e32 v42, v33
	v_mul_f32_e32 v33, 0xbfb8aa3b, v41
	v_exp_f32_e32 v33, v33
	v_cvt_pk_bf16_f32 v38, v34, v35
	v_pk_mul_f32 v[34:35], v[18:19], v[18:19]
	v_pk_mul_f32 v[18:19], v[94:95], v[18:19]
	v_add_f32_e32 v33, 1.0, v33
	v_rcp_f32_e32 v43, v33
	s_nop 0
	v_pk_mul_f32 v[40:41], v[42:43], v[40:41]
	s_nop 0
	v_pk_mul_f32 v[18:19], v[40:41], v[18:19]
	s_nop 0
	v_cvt_pk_bf16_f32 v39, v18, v19
	v_lshl_add_u64 v[18:19], v[36:37], 0, v[198:199]
	v_lshlrev_b32_e32 v36, 16, v126
	global_store_dwordx2 v[18:19], v[38:39], off
	v_pk_mul_f32 v[38:39], v[20:21], v[32:33] op_sel_hi:[1,0]
	v_mul_f32_e32 v33, 0xbfb8aa3b, v36
	v_exp_f32_e32 v33, v33
	v_and_b32_e32 v37, 0xffff0000, v126
	v_pk_mul_f32 v[20:21], v[38:39], v[38:39]
	v_pk_mul_f32 v[38:39], v[88:89], v[38:39]
	v_add_f32_e32 v33, 1.0, v33
	v_rcp_f32_e32 v40, v33
	v_mul_f32_e32 v33, 0xbfb8aa3b, v37
	v_exp_f32_e32 v33, v33
	v_add_f32_e32 v20, v20, v21
	v_add_f32_e32 v21, v34, v35
	v_add_f32_e32 v16, v16, v21
	v_add_f32_e32 v33, 1.0, v33
	v_rcp_f32_e32 v41, v33
	s_nop 0
	v_pk_mul_f32 v[36:37], v[40:41], v[36:37]
	s_nop 0
	v_pk_mul_f32 v[36:37], v[36:37], v[38:39]
	v_lshlrev_b32_e32 v38, 16, v127
	v_pk_mul_f32 v[40:41], v[22:23], v[32:33] op_sel_hi:[1,0]
	v_mul_f32_e32 v33, 0xbfb8aa3b, v38
	v_exp_f32_e32 v33, v33
	v_and_b32_e32 v39, 0xffff0000, v127
	v_pk_mul_f32 v[22:23], v[40:41], v[40:41]
	v_pk_mul_f32 v[40:41], v[90:91], v[40:41]
	v_add_f32_e32 v33, 1.0, v33
	v_rcp_f32_e32 v42, v33
	v_mul_f32_e32 v33, 0xbfb8aa3b, v39
	v_exp_f32_e32 v33, v33
	v_cvt_pk_bf16_f32 v36, v36, v37
	v_add_f32_e32 v22, v22, v23
	v_add_f32_e32 v20, v20, v22
	v_add_f32_e32 v33, 1.0, v33
	v_rcp_f32_e32 v43, v33
	v_add_f32_e32 v16, v16, v20
	v_pk_mul_f32 v[38:39], v[42:43], v[38:39]
	s_nop 0
	v_pk_mul_f32 v[38:39], v[38:39], v[40:41]
	s_nop 0
	v_cvt_pk_bf16_f32 v37, v38, v39
	global_store_dwordx2 v[18:19], v[36:37], off offset:16
	v_lshlrev_b32_e32 v36, 16, v124
	v_pk_mul_f32 v[38:39], v[24:25], v[32:33] op_sel_hi:[1,0]
	v_mul_f32_e32 v33, 0xbfb8aa3b, v36
	v_exp_f32_e32 v33, v33
	v_and_b32_e32 v37, 0xffff0000, v124
	v_pk_mul_f32 v[24:25], v[38:39], v[38:39]
	v_pk_mul_f32 v[38:39], v[84:85], v[38:39]
	v_add_f32_e32 v33, 1.0, v33
	v_rcp_f32_e32 v40, v33
	v_mul_f32_e32 v33, 0xbfb8aa3b, v37
	v_exp_f32_e32 v33, v33
	v_add_f32_e32 v24, v24, v25
	v_add_f32_e32 v33, 1.0, v33
	v_rcp_f32_e32 v41, v33
	s_nop 0
	v_pk_mul_f32 v[36:37], v[40:41], v[36:37]
	s_nop 0
	v_pk_mul_f32 v[36:37], v[36:37], v[38:39]
	v_lshlrev_b32_e32 v38, 16, v125
	v_pk_mul_f32 v[40:41], v[26:27], v[32:33] op_sel_hi:[1,0]
	v_mul_f32_e32 v33, 0xbfb8aa3b, v38
	v_exp_f32_e32 v33, v33
	v_and_b32_e32 v39, 0xffff0000, v125
	v_pk_mul_f32 v[26:27], v[40:41], v[40:41]
	v_pk_mul_f32 v[40:41], v[86:87], v[40:41]
	v_add_f32_e32 v33, 1.0, v33
	v_rcp_f32_e32 v42, v33
	v_mul_f32_e32 v33, 0xbfb8aa3b, v39
	v_exp_f32_e32 v33, v33
	v_cvt_pk_bf16_f32 v36, v36, v37
	v_add_f32_e32 v33, 1.0, v33
	v_rcp_f32_e32 v43, v33
	s_nop 0
	v_pk_mul_f32 v[38:39], v[42:43], v[38:39]
	s_nop 0
	v_pk_mul_f32 v[38:39], v[38:39], v[40:41]
	s_nop 0
	v_cvt_pk_bf16_f32 v37, v38, v39
	global_store_dwordx2 v[18:19], v[36:37], off offset:32
	v_lshlrev_b32_e32 v36, 16, v122
	v_pk_mul_f32 v[38:39], v[28:29], v[32:33] op_sel_hi:[1,0]
	v_mul_f32_e32 v33, 0xbfb8aa3b, v36
	v_exp_f32_e32 v33, v33
	v_and_b32_e32 v37, 0xffff0000, v122
	v_pk_mul_f32 v[28:29], v[38:39], v[38:39]
	v_pk_mul_f32 v[38:39], v[80:81], v[38:39]
	v_add_f32_e32 v33, 1.0, v33
	v_rcp_f32_e32 v40, v33
	v_mul_f32_e32 v33, 0xbfb8aa3b, v37
	v_exp_f32_e32 v33, v33
	v_add_f32_e32 v17, v28, v29
	v_add_f32_e32 v33, 1.0, v33
	v_rcp_f32_e32 v41, v33
	s_nop 0
	v_pk_mul_f32 v[36:37], v[40:41], v[36:37]
	s_nop 0
	v_pk_mul_f32 v[36:37], v[36:37], v[38:39]
	v_lshlrev_b32_e32 v38, 16, v123
	v_pk_mul_f32 v[40:41], v[30:31], v[32:33] op_sel_hi:[1,0]
	v_mul_f32_e32 v33, 0xbfb8aa3b, v38
	v_exp_f32_e32 v33, v33
	v_and_b32_e32 v39, 0xffff0000, v123
	v_pk_mul_f32 v[30:31], v[40:41], v[40:41]
	v_pk_mul_f32 v[40:41], v[82:83], v[40:41]
	v_add_f32_e32 v33, 1.0, v33
	v_rcp_f32_e32 v42, v33
	v_mul_f32_e32 v33, 0xbfb8aa3b, v39
	v_exp_f32_e32 v33, v33
	v_cvt_pk_bf16_f32 v36, v36, v37
	v_add_f32_e32 v33, 1.0, v33
	v_rcp_f32_e32 v43, v33
	s_nop 0
	v_pk_mul_f32 v[38:39], v[42:43], v[38:39]
	s_nop 0
	v_pk_mul_f32 v[38:39], v[38:39], v[40:41]
	s_nop 0
	v_cvt_pk_bf16_f32 v37, v38, v39
	global_store_dwordx2 v[18:19], v[36:37], off offset:48
	v_lshlrev_b32_e32 v36, 16, v120
	v_pk_mul_f32 v[38:39], v[0:1], v[32:33] op_sel_hi:[1,0]
	v_mul_f32_e32 v33, 0xbfb8aa3b, v36
	v_exp_f32_e32 v33, v33
	v_and_b32_e32 v37, 0xffff0000, v120
	v_pk_mul_f32 v[0:1], v[38:39], v[38:39]
	v_pk_mul_f32 v[38:39], v[76:77], v[38:39]
	v_add_f32_e32 v33, 1.0, v33
	v_rcp_f32_e32 v40, v33
	v_mul_f32_e32 v33, 0xbfb8aa3b, v37
	v_exp_f32_e32 v33, v33
	v_add_f32_e32 v0, v0, v1
	v_add_f32_e32 v33, 1.0, v33
	v_rcp_f32_e32 v41, v33
	s_nop 0
	v_pk_mul_f32 v[36:37], v[40:41], v[36:37]
	s_nop 0
	v_pk_mul_f32 v[36:37], v[36:37], v[38:39]
	v_lshlrev_b32_e32 v38, 16, v121
	v_pk_mul_f32 v[40:41], v[2:3], v[32:33] op_sel_hi:[1,0]
	v_mul_f32_e32 v33, 0xbfb8aa3b, v38
	v_exp_f32_e32 v33, v33
	v_and_b32_e32 v39, 0xffff0000, v121
	v_pk_mul_f32 v[2:3], v[40:41], v[40:41]
	v_pk_mul_f32 v[40:41], v[78:79], v[40:41]
	v_add_f32_e32 v33, 1.0, v33
	v_rcp_f32_e32 v42, v33
	v_mul_f32_e32 v33, 0xbfb8aa3b, v39
	v_exp_f32_e32 v33, v33
	v_cvt_pk_bf16_f32 v36, v36, v37
	v_add_f32_e32 v2, v2, v3
	v_add_f32_e32 v0, v0, v2
	v_add_f32_e32 v33, 1.0, v33
	v_rcp_f32_e32 v43, v33
	s_nop 0
	v_pk_mul_f32 v[38:39], v[42:43], v[38:39]
	s_nop 0
	v_pk_mul_f32 v[38:39], v[38:39], v[40:41]
	s_nop 0
	v_cvt_pk_bf16_f32 v37, v38, v39
	global_store_dwordx2 v[18:19], v[36:37], off offset:64
	v_lshlrev_b32_e32 v36, 16, v118
	v_pk_mul_f32 v[38:39], v[4:5], v[32:33] op_sel_hi:[1,0]
	v_mul_f32_e32 v33, 0xbfb8aa3b, v36
	v_exp_f32_e32 v33, v33
	v_and_b32_e32 v37, 0xffff0000, v118
	v_pk_mul_f32 v[4:5], v[38:39], v[38:39]
	v_pk_mul_f32 v[38:39], v[72:73], v[38:39]
	v_add_f32_e32 v33, 1.0, v33
	v_rcp_f32_e32 v40, v33
	v_mul_f32_e32 v33, 0xbfb8aa3b, v37
	v_exp_f32_e32 v33, v33
	v_add_f32_e32 v2, v4, v5
	v_add_f32_e32 v33, 1.0, v33
	v_rcp_f32_e32 v41, v33
	s_nop 0
	v_pk_mul_f32 v[36:37], v[40:41], v[36:37]
	s_nop 0
	v_pk_mul_f32 v[36:37], v[36:37], v[38:39]
	v_lshlrev_b32_e32 v38, 16, v119
	v_pk_mul_f32 v[40:41], v[6:7], v[32:33] op_sel_hi:[1,0]
	v_mul_f32_e32 v33, 0xbfb8aa3b, v38
	v_exp_f32_e32 v33, v33
	v_and_b32_e32 v39, 0xffff0000, v119
	v_pk_mul_f32 v[6:7], v[40:41], v[40:41]
	v_pk_mul_f32 v[40:41], v[74:75], v[40:41]
	v_add_f32_e32 v33, 1.0, v33
	v_rcp_f32_e32 v42, v33
	v_mul_f32_e32 v33, 0xbfb8aa3b, v39
	v_exp_f32_e32 v33, v33
	v_cvt_pk_bf16_f32 v36, v36, v37
	v_add_f32_e32 v1, v6, v7
	v_add_f32_e32 v1, v2, v1
	v_add_f32_e32 v33, 1.0, v33
	v_rcp_f32_e32 v43, v33
	v_pk_mul_f32 v[8:9], v[8:9], v[32:33] op_sel_hi:[1,0]
	v_pk_mul_f32 v[38:39], v[42:43], v[38:39]
	s_nop 0
	v_pk_mul_f32 v[38:39], v[38:39], v[40:41]
	s_nop 0
	v_cvt_pk_bf16_f32 v37, v38, v39
	global_store_dwordx2 v[18:19], v[36:37], off offset:80
	v_lshlrev_b32_e32 v36, 16, v116
	v_mul_f32_e32 v33, 0xbfb8aa3b, v36
	v_exp_f32_e32 v33, v33
	v_and_b32_e32 v37, 0xffff0000, v116
	v_pk_mul_f32 v[38:39], v[8:9], v[8:9]
	v_pk_mul_f32 v[8:9], v[68:69], v[8:9]
	v_add_f32_e32 v33, 1.0, v33
	v_rcp_f32_e32 v40, v33
	v_mul_f32_e32 v33, 0xbfb8aa3b, v37
	v_exp_f32_e32 v33, v33
	v_add_f32_e32 v2, v38, v39
	v_add_f32_e32 v33, 1.0, v33
	v_rcp_f32_e32 v41, v33
	v_pk_mul_f32 v[10:11], v[10:11], v[32:33] op_sel_hi:[1,0]
	v_pk_mul_f32 v[36:37], v[40:41], v[36:37]
	s_nop 0
	v_pk_mul_f32 v[8:9], v[36:37], v[8:9]
	v_lshlrev_b32_e32 v36, 16, v117
	v_cvt_pk_bf16_f32 v8, v8, v9
	v_mul_f32_e32 v9, 0xbfb8aa3b, v36
	v_exp_f32_e32 v9, v9
	v_and_b32_e32 v37, 0xffff0000, v117
	v_pk_mul_f32 v[40:41], v[10:11], v[10:11]
	v_pk_mul_f32 v[10:11], v[70:71], v[10:11]
	v_add_f32_e32 v9, 1.0, v9
	v_rcp_f32_e32 v42, v9
	v_mul_f32_e32 v9, 0xbfb8aa3b, v37
	v_exp_f32_e32 v9, v9
	s_nop 0
	v_add_f32_e32 v9, 1.0, v9
	v_rcp_f32_e32 v43, v9
	s_nop 0
	v_pk_mul_f32 v[36:37], v[42:43], v[36:37]
	s_nop 0
	v_pk_mul_f32 v[10:11], v[36:37], v[10:11]
	s_nop 0
	v_cvt_pk_bf16_f32 v9, v10, v11
	global_store_dwordx2 v[18:19], v[8:9], off offset:96
	v_lshlrev_b32_e32 v8, 16, v114
	v_pk_mul_f32 v[10:11], v[12:13], v[32:33] op_sel_hi:[1,0]
	v_mul_f32_e32 v33, 0xbfb8aa3b, v8
	v_exp_f32_e32 v33, v33
	v_and_b32_e32 v9, 0xffff0000, v114
	v_pk_mul_f32 v[12:13], v[10:11], v[10:11]
	v_pk_mul_f32 v[10:11], v[64:65], v[10:11]
	v_add_f32_e32 v33, 1.0, v33
	v_rcp_f32_e32 v36, v33
	v_mul_f32_e32 v33, 0xbfb8aa3b, v9
	v_exp_f32_e32 v33, v33
	s_nop 0
	v_add_f32_e32 v33, 1.0, v33
	v_rcp_f32_e32 v37, v33
	v_pk_mul_f32 v[14:15], v[14:15], v[32:33] op_sel_hi:[1,0]
	v_pk_mul_f32 v[8:9], v[36:37], v[8:9]
	s_nop 0
	v_pk_mul_f32 v[8:9], v[8:9], v[10:11]
	v_pk_mul_f32 v[32:33], v[14:15], v[14:15]
	v_cvt_pk_bf16_f32 v8, v8, v9
	v_add_f32_e32 v9, v26, v27
	v_add_f32_e32 v9, v24, v9
	v_add_f32_e32 v9, v9, v16
	v_add_f32_e32 v16, v30, v31
	v_add_f32_e32 v16, v17, v16
	v_add_f32_e32 v9, v16, v9
	v_add_f32_e32 v0, v0, v9
	v_add_f32_e32 v0, v1, v0
	v_add_f32_e32 v1, v40, v41
	v_add_f32_e32 v1, v2, v1
	v_add_f32_e32 v0, v1, v0
	v_add_f32_e32 v1, v32, v33
	v_add_f32_e32 v2, v12, v13
	v_lshlrev_b32_e32 v10, 16, v115
	v_add_f32_e32 v1, v2, v1
	v_add_f32_e32 v0, v1, v0
	v_mul_f32_e32 v1, 0xbfb8aa3b, v10
	v_exp_f32_e32 v1, v1
	v_and_b32_e32 v11, 0xffff0000, v115
	v_pk_mul_f32 v[4:5], v[66:67], v[14:15]
	v_add_f32_e32 v1, 1.0, v1
	v_rcp_f32_e32 v2, v1
	v_mul_f32_e32 v1, 0xbfb8aa3b, v11
	v_exp_f32_e32 v1, v1
	s_nop 0
	v_add_f32_e32 v1, 1.0, v1
	v_rcp_f32_e32 v3, v1
	ds_bpermute_b32 v1, v133, v0
	v_pk_mul_f32 v[2:3], v[2:3], v[10:11]
	s_nop 0
	v_pk_mul_f32 v[2:3], v[2:3], v[4:5]
	s_nop 0
	v_cvt_pk_bf16_f32 v9, v2, v3
	global_store_dwordx2 v[18:19], v[8:9], off offset:112
	s_and_saveexec_b64 s[0:1], vcc
	s_cbranch_execz .LBB0_443
	s_add_u32 s4, s28, s4
	s_addc_u32 s5, s29, s5
	s_waitcnt lgkmcnt(0)
	v_add_f32_e32 v2, v0, v1
	v_lshlrev_b64 v[0:1], 5, v[112:113]
	v_lshl_add_u64 v[0:1], s[4:5], 0, v[0:1]
	v_lshlrev_b32_e32 v198, 2, v129
	v_lshl_add_u64 v[0:1], v[0:1], 0, v[198:199]
	global_store_dword v[0:1], v2, off
